# latent attention item prologue: the two batches of staging loads overlap (second batch issued before the first wait)
# baseline (speedup 1.0000x reference)
.LBB0_206:
	s_andn2_b64 vcc, exec, s[0:1]
	s_cbranch_vccnz .LBB0_149
	v_mov_b32_e32 v20, v224
	s_ashr_i32 s2, s41, 4
	s_lshl_b32 s1, s41, 7
	v_readfirstlane_b32 s31, v20
	s_bfe_u32 s58, s31, 0x20006
	s_lshl_b32 s0, s2, 11
	s_and_b32 s1, s1, 0x780
	s_or_b32 s0, s0, s1
	s_lshl_b32 s1, s58, 5
	v_and_b32_e32 v21, 31, v20
	s_or_b32 s0, s1, s0
	v_or_b32_e32 v160, s0, v21
	s_ashr_i32 s59, s31, 8
	v_ashrrev_i32_e32 v161, 31, v160
	v_lshlrev_b64 v[0:1], 11, v[160:161]
	s_lshl_b32 s0, s59, 6
	v_bfe_u32 v163, v20, 5, 1
	v_lshl_add_u64 v[0:1], s[34:35], 0, v[0:1]
	s_ashr_i32 s1, s0, 31
	v_lshl_add_u64 v[0:1], s[0:1], 1, v[0:1]
	v_lshlrev_b32_e32 v192, 4, v163
	v_lshl_add_u64 v[0:1], v[0:1], 0, v[192:193]
	global_load_dwordx4 v[112:115], v[0:1], off
	global_load_dwordx4 v[116:119], v[0:1], off offset:32
	global_load_dwordx4 v[120:123], v[0:1], off offset:64
	s_lshl_b32 s0, s2, 3
	global_load_dwordx4 v[124:127], v[0:1], off offset:96
	s_or_b32 s0, s0, s54
	s_lshl_b32 s1, s0, 1
	s_mul_i32 s4, s0, 0x90000
	s_mul_hi_i32 s1, s1, 0x48000
	s_add_u32 s2, s56, s4
	s_addc_u32 s3, s57, s1
	s_mul_hi_i32 s0, s0, 0x90000
	s_add_u32 s48, s44, s4
	s_addc_u32 s49, s45, s0
	s_add_u32 s62, s2, 0x48000
	s_addc_u32 s63, s3, 0
	s_add_u32 s4, s48, 0x48000
	s_addc_u32 s5, s49, 0
	s_and_b32 s0, s41, -16
	s_add_i32 s0, s0, s75
	s_add_i32 s0, s0, s59
	s_ashr_i32 s1, s0, 31
	v_ashrrev_i32_e32 v2, 3, v20
	v_and_b32_e32 v3, 7, v20
	s_lshl_b64 s[0:1], s[0:1], 2
	v_readlane_b32 s9, v252, 46
	v_lshlrev_b32_e32 v165, 7, v2
	v_lshlrev_b32_e32 v3, 4, v3
	s_add_u32 s0, s9, s0
	v_readlane_b32 s9, v252, 47
	v_or_b32_e32 v26, v165, v3
	s_addc_u32 s1, s9, s1
	global_load_dwordx4 v[128:131], v26, s[2:3]
	global_load_dwordx4 v[132:135], v26, s[62:63]
	global_load_dword v27, v193, s[0:1]
	v_mul_lo_u32 v2, v2, s7
	v_or_b32_e32 v167, v2, v3
	v_lshrrev_b32_e32 v22, 4, v20
	v_and_b32_e32 v24, 6, v20
	v_bfe_u32 v23, v20, 4, 3
	v_bitop3_b32 v25, v22, v20, 7 bitop3:0x28
	v_lshl_or_b32 v170, v25, 4, v165
	v_lshlrev_b32_e32 v21, 7, v21
	v_mov_b32_e32 v168, 0
	v_mov_b32_e32 v148, 0
	v_and_b32_e32 v166, 63, v20
	s_mov_b32 s64, 0
	v_add_u32_e32 v174, 0, v21
	v_add_u32_e32 v178, 0x4000, v26
	s_mov_b32 s41, 0
	v_mov_b32_e32 v149, v148
	v_mov_b32_e32 v150, v148
	v_mov_b32_e32 v151, v148
	v_mov_b32_e32 v144, v148
	v_mov_b32_e32 v145, v148
	v_mov_b32_e32 v146, v148
	v_mov_b32_e32 v147, v148
	v_mov_b32_e32 v140, v148
	v_mov_b32_e32 v141, v148
	v_mov_b32_e32 v142, v148
	v_mov_b32_e32 v143, v148
	v_mov_b32_e32 v136, v148
	v_mov_b32_e32 v137, v148
	v_mov_b32_e32 v138, v148
	v_mov_b32_e32 v139, v148
	v_mov_b32_e32 v48, 0
	v_mov_b32_e32 v49, v168
	v_mov_b32_e32 v50, v168
	v_mov_b32_e32 v51, v168
	v_mov_b32_e32 v52, v168
	v_mov_b32_e32 v53, v168
	v_mov_b32_e32 v54, v168
	v_mov_b32_e32 v55, v168
	v_mov_b32_e32 v56, v168
	v_mov_b32_e32 v57, v168
	v_mov_b32_e32 v58, v168
	v_mov_b32_e32 v59, v168
	v_mov_b32_e32 v60, v168
	v_mov_b32_e32 v61, v168
	v_mov_b32_e32 v62, v168
	v_mov_b32_e32 v63, v168
	global_load_dwordx4 v[80:83], v167, s[48:49]
	global_load_dwordx4 v[84:87], v167, s[4:5]
	v_add_u32_e32 v96, 0x2000, v26
	global_load_dwordx4 v[88:91], v96, s[2:3]
	global_load_dwordx4 v[92:95], v96, s[62:63]
	s_waitcnt vmcnt(4)
	v_and_b32_e32 v1, 0xffff0000, v112
	v_and_b32_e32 v3, 0xffff0000, v113
	v_lshlrev_b32_e32 v0, 16, v112
	v_lshlrev_b32_e32 v2, 16, v113
	v_and_b32_e32 v5, 0xffff0000, v114
	v_mul_f32_e32 v1, v1, v1
	v_mul_f32_e32 v3, v3, v3
	v_lshlrev_b32_e32 v4, 16, v114
	v_and_b32_e32 v7, 0xffff0000, v115
	v_mul_f32_e32 v5, v5, v5
	v_fmac_f32_e32 v1, v0, v0
	v_fmac_f32_e32 v3, v2, v2
	v_lshlrev_b32_e32 v6, 16, v115
	v_and_b32_e32 v9, 0xffff0000, v116
	v_mul_f32_e32 v7, v7, v7
	v_fmac_f32_e32 v5, v4, v4
	v_add_f32_e32 v0, v1, v3
	v_lshlrev_b32_e32 v8, 16, v116
	v_and_b32_e32 v11, 0xffff0000, v117
	v_mul_f32_e32 v9, v9, v9
	v_fmac_f32_e32 v7, v6, v6
	v_add_f32_e32 v0, v5, v0
	v_lshlrev_b32_e32 v10, 16, v117
	v_and_b32_e32 v13, 0xffff0000, v118
	v_mul_f32_e32 v11, v11, v11
	v_fmac_f32_e32 v9, v8, v8
	v_add_f32_e32 v0, v7, v0
	v_lshlrev_b32_e32 v12, 16, v118
	v_and_b32_e32 v15, 0xffff0000, v119
	v_mul_f32_e32 v13, v13, v13
	v_fmac_f32_e32 v11, v10, v10
	v_add_f32_e32 v0, v9, v0
	v_lshlrev_b32_e32 v14, 16, v119
	v_mul_f32_e32 v15, v15, v15
	v_fmac_f32_e32 v13, v12, v12
	v_add_f32_e32 v0, v11, v0
	v_fmac_f32_e32 v15, v14, v14
	v_add_f32_e32 v0, v13, v0
	v_add_f32_e32 v17, v15, v0
	v_and_b32_e32 v18, 0xffff0000, v120
	v_lshlrev_b32_e32 v16, 16, v120
	v_mul_f32_e32 v18, v18, v18
	v_fmac_f32_e32 v18, v16, v16
	v_add_f32_e32 v16, v18, v17
	v_and_b32_e32 v18, 0xffff0000, v121
	v_lshlrev_b32_e32 v17, 16, v121
	v_mul_f32_e32 v18, v18, v18
	v_fmac_f32_e32 v18, v17, v17
	v_add_f32_e32 v28, v18, v16
	v_and_b32_e32 v19, 0xffff0000, v123
	v_and_b32_e32 v18, 0xffff0000, v122
	v_lshlrev_b32_e32 v17, 16, v123
	v_lshlrev_b32_e32 v16, 16, v122
	v_pk_mul_f32 v[18:19], v[18:19], v[18:19]
	v_mov_b32_e32 v32, 0
	v_pk_fma_f32 v[16:17], v[16:17], v[16:17], v[18:19]
	v_and_b32_e32 v19, 0xffff0000, v125
	v_add_f32_e32 v16, v16, v28
	v_and_b32_e32 v18, 0xffff0000, v124
	v_add_f32_e32 v28, v17, v16
	v_lshlrev_b32_e32 v17, 16, v125
	v_lshlrev_b32_e32 v16, 16, v124
	v_pk_mul_f32 v[18:19], v[18:19], v[18:19]
	v_mov_b32_e32 v33, v168
	v_pk_fma_f32 v[16:17], v[16:17], v[16:17], v[18:19]
	v_and_b32_e32 v19, 0xffff0000, v127
	v_add_f32_e32 v16, v16, v28
	v_and_b32_e32 v18, 0xffff0000, v126
	v_add_f32_e32 v28, v17, v16
	v_lshlrev_b32_e32 v17, 16, v127
	v_lshlrev_b32_e32 v16, 16, v126
	v_pk_mul_f32 v[18:19], v[18:19], v[18:19]
	v_mov_b32_e32 v34, v168
	v_pk_fma_f32 v[16:17], v[16:17], v[16:17], v[18:19]
	v_and_b32_e32 v18, 64, v229
	v_add_f32_e32 v16, v16, v28
	v_add_f32_e32 v16, v17, v16
	v_xor_b32_e32 v17, 32, v229
	v_add_u32_e32 v18, 64, v18
	v_cmp_lt_i32_e32 vcc, v17, v18
	v_lshlrev_b32_e32 v19, 3, v20
	v_bitop3_b32 v18, v22, v24, 7 bitop3:0x6c
	v_cndmask_b32_e32 v17, v229, v17, vcc
	v_lshlrev_b32_e32 v164, 2, v17
	ds_bpermute_b32 v17, v164, v16
	v_and_b32_e32 v19, 8, v19
	v_bitop3_b32 v22, v24, v23, 1 bitop3:0x36
	v_lshl_or_b32 v172, v18, 4, v19
	v_lshl_or_b32 v169, v22, 4, v19
	s_waitcnt lgkmcnt(0)
	v_add_f32_e32 v16, v16, v17
	v_mul_f32_e32 v16, v27, v16
	v_mul_f32_e32 v17, 0x4f800000, v16
	v_cmp_gt_f32_e32 vcc, s92, v16
	v_mov_b32_e32 v35, v168
	v_mov_b32_e32 v36, v168
	v_cndmask_b32_e32 v16, v16, v17, vcc
	v_sqrt_f32_e32 v17, v16
	v_mov_b32_e32 v37, v168
	v_mov_b32_e32 v38, v168
	v_mov_b32_e32 v39, v168
	v_add_u32_e32 v18, -1, v17
	v_fma_f32 v19, -v18, v17, v16
	v_cmp_ge_f32_e64 s[0:1], 0, v19
	v_add_u32_e32 v19, 1, v17
	v_mov_b32_e32 v40, v168
	v_cndmask_b32_e64 v18, v17, v18, s[0:1]
	v_fma_f32 v17, -v19, v17, v16
	v_cmp_lt_f32_e64 s[0:1], 0, v17
	v_mov_b32_e32 v41, v168
	v_mov_b32_e32 v42, v168
	v_cndmask_b32_e64 v17, v18, v19, s[0:1]
	v_mul_f32_e32 v18, 0x37800000, v17
	v_cndmask_b32_e32 v17, v17, v18, vcc
	v_cmp_class_f32_e32 vcc, v16, v228
	v_add_u32_e32 v18, 0, v165
	v_add_u32_e32 v19, v18, v172
	v_cndmask_b32_e32 v16, v17, v16, vcc
	v_fmamk_f32 v16, v16, 0x3f828f5c, v227
	v_add_u32_e32 v17, 0, v170
	v_xor_b32_e32 v64, 0x80000000, v16
	v_lshrrev_b32_e32 v16, 1, v20
	s_lshl_b32 s0, s59, 13
	ds_write_b128 v17, v[128:131]
	ds_write_b128 v17, v[132:135] offset:8192
	s_waitcnt vmcnt(3)
	ds_write_b64 v19, v[80:81] offset:49152
	v_add_u32_e32 v0, v18, v169
	s_waitcnt vmcnt(2)
	ds_write_b64 v19, v[84:85] offset:57344
	ds_write2st64_b64 v0, v[82:83], v[86:87] offset0:96 offset1:112
	s_waitcnt vmcnt(1)
	ds_write_b128 v17, v[88:91] offset:16384
	s_waitcnt vmcnt(0)
	ds_write_b128 v17, v[92:95] offset:24576
	s_add_i32 s0, s0, 0
	v_bitop3_b32 v0, v163, v16, 7 bitop3:0x78
	v_add_u32_e32 v177, s0, v21
	v_lshlrev_b32_e32 v176, 4, v0
	v_add_u32_e32 v4, v177, v176
	s_waitcnt lgkmcnt(0)
	s_barrier
	ds_read_b128 v[0:3], v4
	ds_read_b128 v[4:7], v4 offset:4096
	v_mov_b32_e32 v65, v64
	v_mov_b32_e32 v66, v64
	v_mov_b32_e32 v67, v64
	v_mov_b32_e32 v68, v64
	v_mov_b32_e32 v69, v64
	v_mov_b32_e32 v70, v64
	v_mov_b32_e32 v71, v64
	v_mov_b32_e32 v72, v64
	v_mov_b32_e32 v73, v64
	v_mov_b32_e32 v74, v64
	v_mov_b32_e32 v75, v64
	v_mov_b32_e32 v76, v64
	v_mov_b32_e32 v77, v64
	v_mov_b32_e32 v78, v64
	v_mov_b32_e32 v79, v64
	v_bfe_u32 v16, v20, 1, 3
	v_mov_b32_e32 v43, v168
	s_waitcnt lgkmcnt(1)
	v_mfma_f32_32x32x16_bf16 v[96:111], v[0:3], v[112:115], v[64:79]
	v_bitop3_b32 v0, v163, v16, 2 bitop3:0x36
	v_lshlrev_b32_e32 v175, 4, v0
	v_add_u32_e32 v8, v177, v175
	ds_read_b128 v[0:3], v8
	ds_read_b128 v[8:11], v8 offset:4096
	v_mov_b32_e32 v44, v168
	v_mov_b32_e32 v45, v168
	v_mov_b32_e32 v46, v168
	s_waitcnt lgkmcnt(2)
	v_mfma_f32_32x32x16_bf16 v[80:95], v[4:7], v[112:115], v[64:79]
	v_mov_b32_e32 v47, v168
	v_mov_b32_e32 v20, v168
	v_mov_b32_e32 v21, v168
	v_mov_b32_e32 v22, v168
	v_mov_b32_e32 v23, v168
	v_mov_b32_e32 v24, v168
	v_mov_b32_e32 v25, v168
	s_waitcnt lgkmcnt(1)
	v_mfma_f32_32x32x16_bf16 v[96:111], v[0:3], v[116:119], v[96:111]
	v_bitop3_b32 v0, v163, v16, 4 bitop3:0x36
	v_lshlrev_b32_e32 v173, 4, v0
	v_add_u32_e32 v12, v177, v173
	ds_read_b128 v[0:3], v12
	ds_read_b128 v[12:15], v12 offset:4096
	v_mov_b32_e32 v26, v168
	v_mov_b32_e32 v27, v168
	v_mov_b32_e32 v28, v168
	s_waitcnt lgkmcnt(2)
	v_mfma_f32_32x32x16_bf16 v[80:95], v[8:11], v[116:119], v[80:95]
	v_mov_b32_e32 v29, v168
	v_mov_b32_e32 v30, v168
	v_mov_b32_e32 v31, v168
	v_mov_b32_e32 v4, v168
	v_mov_b32_e32 v5, v168
	v_mov_b32_e32 v6, v168
	v_mov_b32_e32 v7, v168
	s_waitcnt lgkmcnt(1)
	v_mfma_f32_32x32x16_bf16 v[96:111], v[0:3], v[120:123], v[96:111]
	v_bitop3_b32 v0, v163, v16, 6 bitop3:0x36
	v_lshlrev_b32_e32 v171, 4, v0
	v_add_u32_e32 v16, v177, v171
	ds_read_b128 v[0:3], v16
	ds_read_b128 v[16:19], v16 offset:4096
	v_mov_b32_e32 v8, v168
	v_mov_b32_e32 v9, v168
	v_mov_b32_e32 v10, v168
	s_waitcnt lgkmcnt(2)
	v_mfma_f32_32x32x16_bf16 v[80:95], v[12:15], v[120:123], v[80:95]
	v_mov_b32_e32 v11, v168
	v_mov_b32_e32 v12, v168
	v_mov_b32_e32 v13, v168
	v_mov_b32_e32 v14, v168
	v_mov_b32_e32 v15, v168
	s_waitcnt lgkmcnt(1)
	v_mfma_f32_32x32x16_bf16 v[96:111], v[0:3], v[124:127], v[96:111]
	v_mov_b32_e32 v0, 0
	v_mov_b32_e32 v1, v168
	v_mov_b32_e32 v2, v168
	v_mov_b32_e32 v3, v168
	s_waitcnt lgkmcnt(0)
	v_mfma_f32_32x32x16_bf16 v[80:95], v[16:19], v[124:127], v[80:95]
	v_mov_b32_e32 v16, 0
	v_mov_b32_e32 v17, v168
	v_mov_b32_e32 v18, v168
	v_mov_b32_e32 v19, v168
